# attention PV section: exps/adds re-spaced evenly around the 16 PV MFMAs (2 exp + 2 add per gap); peel: wait in front of first QK MFMA leaves the K(2)/V(1) DMAs in flight
# baseline (speedup 1.0000x reference)
; template <bool FIRST, bool HAS_PREV> ...
;     ...
;     { const float nm = FIRST ? 0.f : -st.mrun;
; #pragma unroll
;       for (int i = 0; i < 16; ++i) { c0[i] = nm; c1[i] = nm; } }
; #pragma unroll
;     for (int ks = 0; ks < 2; ++ks) { DSR128(kf[2 * ks], ka[ks], 0); DSR128(kf[2 * ks + 1], ka[ks], 4096); }
;     asm volatile("s_waitcnt lgkmcnt(0)" : "+v"(kf[0]), "+v"(kf[1]), "+v"(kf[2]), "+v"(kf[3]));
; #pragma unroll
;     for (int ks = 0; ks < 2; ++ks) {
;         c0 = __builtin_amdgcn_mfma_f32_32x32x16_bf16(kf[2 * ks], qr[ks], c0, 0, 0, 0);
;         c1 = __builtin_amdgcn_mfma_f32_32x32x16_bf16(kf[2 * ks + 1], qr[ks], c1, 0, 0, 0);
;     }
;     __builtin_amdgcn_sched_barrier(0);
;     { bf16x8 kg[4];
; #pragma unroll
;       for (int ks = 0; ks < 2; ++ks) { DSR128(kg[2 * ks], ka[2 + ks], 0); DSR128(kg[2 * ks + 1], ka[2 + ks], 4096); }
;       asm volatile("s_waitcnt lgkmcnt(0)" : "+v"(kg[0]), "+v"(kg[1]), "+v"(kg[2]), "+v"(kg[3]));
; #pragma unroll
;       for (int ks = 0; ks < 2; ++ks) {
;           c0 = __builtin_amdgcn_mfma_f32_32x32x16_bf16(kg[2 * ks], qr[2 + ks], c0, 0, 0, 0);
; __device__ __forceinline__ void attn_unit(LAS unsigned char* lds, const bf16* __restrict__ Qb, const bf16* __restrict__ Kb, const bf16* __restrict__ VT, bf16* __restrict__ Y,
;                                           const float* __restrict__ gsub, float lam, int b, int h, int qb, float* o1scr) {
;     ...
;         const int c1 = 256 * (h >> 1) + 32 * (2 * (h & 1) + mp);
;         const bf16* qp = Qb + (tok0 + (size_t)qb * 256 + wid * 32 + r32) * 512 + c1 + 8 * hi;
;         bf16x8 qr[4];
;         qr[0] = *(const bf16x8*)(qp); qr[1] = *(const bf16x8*)(qp + 16); qr[2] = *(const bf16x8*)(qp + 128); qr[3] = *(const bf16x8*)(qp + 144);
;         const bf16* kp = Kb + (tok0 + lrow) * 512 + c1 + kcol;
;         const bf16* vp = VT + ((size_t)((b * 4 + h) * 32) * 128 + lrow) * 64 + lc * 8;
;         ATT_DMA(kp, 0); ATT_DMA(vp, VB0); ATT_DMA(vp + 4096, VB0 + 8192); ATT_DMA(kp + (size_t)64 * 512, KSL);
;         ATT_WAITBAR(0);
; #pragma unroll
;         for (int e = 0; e < 4; ++e)
; #pragma unroll
;             for (int i = 0; i < 16; ++i) o[e][i] = 0.f;
;         AttnState st; st.mrun = 0.f; st.l = 0.f;
;         bf16x8 pbp[4];
;         f32x16 sA, sB;
;         int s0 = 0, s1 = 1, s2 = 2;
;     ...
;         ATT_STEP(0, true, false);
.LBB0_560:
	s_or_b32 s44, s73, s44
	s_lshl_b64 s[82:83], s[44:45], 1
	v_lshl_add_u64 v[0:1], v[176:177], 0, s[82:83]
	global_load_dwordx4 v[96:99], v[0:1], off
	s_mov_b32 m0, s33
	v_lshl_add_u64 v[2:3], v[180:181], 0, s[82:83]
	global_load_dwordx4 v[100:103], v[0:1], off offset:32
	global_load_dwordx4 v[104:107], v[0:1], off offset:256
	global_load_dwordx4 v[108:111], v[0:1], off offset:288
	v_lshl_add_u64 v[0:1], v[2:3], 0, s[62:63]
	global_load_lds_dwordx4 v[2:3], off
	s_mov_b32 m0, s89
	v_lshl_add_u64 v[2:3], v[2:3], 0, s[64:65]
	global_load_lds_dwordx4 v[184:185], off
	s_mov_b32 m0, s90
	s_mov_b32 s44, s45
	global_load_lds_dwordx4 v[186:187], off
	s_mov_b32 m0, s91
	s_mov_b32 s46, s45
	global_load_lds_dwordx4 v[0:1], off
	s_waitcnt vmcnt(0) lgkmcnt(0)
	s_barrier
	s_mov_b32 m0, s92
	s_mov_b32 s47, s45
	global_load_lds_dwordx4 v[2:3], off
	s_mov_b32 m0, s93
	s_mov_b32 s48, s45
	global_load_lds_dwordx4 v[188:189], off
	s_mov_b32 m0, s94
	s_mov_b32 s49, s45
	global_load_lds_dwordx4 v[190:191], off
	ds_read_b128 v[0:3], v217 offset:0
	ds_read_b128 v[4:7], v217 offset:0x1000
	ds_read_b128 v[8:11], v218 offset:0
	ds_read_b128 v[48:51], v218 offset:0x1000
	s_mov_b32 s50, s45
	s_waitcnt lgkmcnt(0)
	s_mov_b32 s51, s45
	s_mov_b32 s52, s45
	s_mov_b32 s53, s45
	s_mov_b32 s54, s45
	s_mov_b32 s55, s45
	s_mov_b32 s56, s45
	s_mov_b32 s57, s45
	s_mov_b32 s58, s45
	s_mov_b32 s59, s45
	s_mov_b32 s74, 1
	s_waitcnt vmcnt(3)
	v_mfma_f32_32x32x16_bf16 v[16:31], v[0:3], v[96:99], 0
	v_mfma_f32_32x32x16_bf16 v[32:47], v[4:7], v[96:99], 0
	v_mfma_f32_32x32x16_bf16 v[16:31], v[8:11], v[100:103], v[16:31]
	v_mov_b64_e32 v[0:1], s[44:45]
	v_mov_b64_e32 v[2:3], s[46:47]
	v_mov_b64_e32 v[4:5], s[48:49]
	v_mov_b64_e32 v[6:7], s[50:51]
	v_mov_b64_e32 v[8:9], s[52:53]
	v_mov_b64_e32 v[10:11], s[54:55]
	v_mov_b64_e32 v[12:13], s[56:57]
	v_mfma_f32_32x32x16_bf16 v[32:47], v[48:51], v[100:103], v[32:47]
	v_mov_b64_e32 v[14:15], s[58:59]
	ds_read_b128 v[48:51], v219 offset:0
	ds_read_b128 v[52:55], v219 offset:0x1000
	ds_read_b128 v[56:59], v220 offset:0
	ds_read_b128 v[60:63], v220 offset:0x1000
	s_nop 0
	s_waitcnt lgkmcnt(0)
	s_nop 0
	v_mfma_f32_32x32x16_bf16 v[16:31], v[48:51], v[104:107], v[16:31]
	v_mfma_f32_32x32x16_bf16 v[32:47], v[52:55], v[104:107], v[32:47]
	v_mfma_f32_32x32x16_bf16 v[16:31], v[56:59], v[108:111], v[16:31]
	v_mfma_f32_32x32x16_bf16 v[32:47], v[60:63], v[108:111], v[32:47]
	s_nop 11
	v_max_f32_e32 v48, v33, v33
	v_max_f32_e32 v49, v17, v17
	v_max_f32_e32 v48, v49, v48
	v_max_f32_e32 v49, v34, v34
	v_max_f32_e32 v50, v18, v18
	v_max_f32_e32 v49, v50, v49
	v_max_f32_e32 v50, v35, v35
	v_max_f32_e32 v51, v19, v19
	v_max3_f32 v48, v16, v32, v48
	v_max_f32_e32 v50, v51, v50
	v_max3_f32 v48, v48, v49, v50
	v_max_f32_e32 v49, v36, v36
	v_max_f32_e32 v50, v20, v20
	v_max_f32_e32 v49, v50, v49
	v_max_f32_e32 v50, v37, v37
	v_max_f32_e32 v51, v21, v21
	v_max_f32_e32 v50, v51, v50
	v_max3_f32 v48, v48, v49, v50
	v_max_f32_e32 v49, v38, v38
	v_max_f32_e32 v50, v22, v22
	v_max_f32_e32 v49, v50, v49
	v_max_f32_e32 v50, v39, v39
	v_max_f32_e32 v51, v23, v23
	v_max_f32_e32 v50, v51, v50
	v_max3_f32 v48, v48, v49, v50
	v_max_f32_e32 v49, v40, v40
	v_max_f32_e32 v50, v24, v24
	v_max_f32_e32 v49, v50, v49
	v_max_f32_e32 v50, v41, v41
	v_max_f32_e32 v51, v25, v25
	v_max_f32_e32 v50, v51, v50
	v_max3_f32 v48, v48, v49, v50
	v_max_f32_e32 v49, v42, v42
	v_max_f32_e32 v50, v26, v26
	v_max_f32_e32 v49, v50, v49
	v_max_f32_e32 v50, v43, v43
	v_max_f32_e32 v51, v27, v27
	v_max_f32_e32 v50, v51, v50
	v_max3_f32 v48, v48, v49, v50
	v_max_f32_e32 v49, v44, v44
	v_max_f32_e32 v50, v28, v28
	v_max_f32_e32 v49, v50, v49
	v_max_f32_e32 v50, v45, v45
	v_max_f32_e32 v51, v29, v29
	v_max_f32_e32 v50, v51, v50
	v_max3_f32 v48, v48, v49, v50
	v_max_f32_e32 v49, v46, v46
	v_max_f32_e32 v50, v30, v30
	v_max_f32_e32 v49, v50, v49
	v_max_f32_e32 v50, v47, v47
	v_max_f32_e32 v51, v31, v31
	v_max_f32_e32 v50, v51, v50
	v_max3_f32 v48, v48, v49, v50
	v_mov_b32_e32 v49, v48
	s_nop 1
	v_permlane32_swap_b32_e32 v48, v49
	v_max_f32_e32 v49, v49, v49
	v_max_f32_e32 v48, v48, v48
	v_max_f32_e32 v49, v48, v49
	v_sub_f32_e32 v16, v16, v49
	v_sub_f32_e32 v32, v32, v49
	v_exp_f32_e32 v16, v16
	v_sub_f32_e32 v17, v17, v49
	v_exp_f32_e32 v32, v32
	v_sub_f32_e32 v33, v33, v49
	v_exp_f32_e32 v17, v17
	v_sub_f32_e32 v18, v18, v49
	v_exp_f32_e32 v33, v33
	v_sub_f32_e32 v34, v34, v49
	v_add_f32_e32 v48, 0, v16
	v_exp_f32_e32 v18, v18
	v_sub_f32_e32 v19, v19, v49
	v_add_f32_e32 v48, v32, v48
	v_exp_f32_e32 v34, v34
	v_sub_f32_e32 v35, v35, v49
	v_add_f32_e32 v48, v17, v48
	v_exp_f32_e32 v19, v19
	v_sub_f32_e32 v20, v20, v49
	v_add_f32_e32 v48, v33, v48
	v_exp_f32_e32 v35, v35
	v_sub_f32_e32 v36, v36, v49
	v_add_f32_e32 v48, v18, v48
	v_exp_f32_e32 v20, v20
	v_sub_f32_e32 v21, v21, v49
	v_add_f32_e32 v48, v34, v48
	v_exp_f32_e32 v36, v36
	v_sub_f32_e32 v37, v37, v49
	v_add_f32_e32 v48, v19, v48
	v_exp_f32_e32 v21, v21
	v_sub_f32_e32 v22, v22, v49
	v_add_f32_e32 v48, v35, v48
	v_exp_f32_e32 v37, v37
	v_sub_f32_e32 v38, v38, v49
	v_add_f32_e32 v48, v20, v48
	v_exp_f32_e32 v22, v22
	v_sub_f32_e32 v23, v23, v49
	v_add_f32_e32 v48, v36, v48
	v_exp_f32_e32 v38, v38
	v_sub_f32_e32 v39, v39, v49
	v_add_f32_e32 v48, v21, v48
	v_exp_f32_e32 v23, v23
	v_sub_f32_e32 v24, v24, v49
	v_add_f32_e32 v48, v37, v48
	v_exp_f32_e32 v39, v39
	v_sub_f32_e32 v40, v40, v49
	v_add_f32_e32 v48, v22, v48
	v_exp_f32_e32 v24, v24
	v_sub_f32_e32 v25, v25, v49
	v_add_f32_e32 v48, v38, v48
	v_exp_f32_e32 v40, v40
	v_sub_f32_e32 v41, v41, v49
	v_add_f32_e32 v48, v23, v48
	v_exp_f32_e32 v25, v25
	v_sub_f32_e32 v26, v26, v49
	v_add_f32_e32 v48, v39, v48
	v_exp_f32_e32 v41, v41
	v_sub_f32_e32 v42, v42, v49
	v_add_f32_e32 v48, v24, v48
	v_exp_f32_e32 v26, v26
	v_sub_f32_e32 v27, v27, v49
	v_add_f32_e32 v48, v40, v48
	v_exp_f32_e32 v42, v42
	v_sub_f32_e32 v43, v43, v49
	v_add_f32_e32 v48, v25, v48
	v_exp_f32_e32 v27, v27
	v_sub_f32_e32 v28, v28, v49
	v_add_f32_e32 v48, v41, v48
	v_exp_f32_e32 v43, v43
	v_sub_f32_e32 v44, v44, v49
	v_add_f32_e32 v48, v26, v48
	v_exp_f32_e32 v28, v28
	v_sub_f32_e32 v29, v29, v49
	v_add_f32_e32 v48, v42, v48
	v_exp_f32_e32 v44, v44
	v_sub_f32_e32 v45, v45, v49
	v_add_f32_e32 v48, v27, v48
	v_exp_f32_e32 v29, v29
	v_sub_f32_e32 v30, v30, v49
	v_add_f32_e32 v48, v43, v48
	v_exp_f32_e32 v45, v45
	v_sub_f32_e32 v46, v46, v49
	v_add_f32_e32 v48, v28, v48
	v_exp_f32_e32 v30, v30
	v_sub_f32_e32 v31, v31, v49
	v_add_f32_e32 v48, v44, v48
	v_exp_f32_e32 v46, v46
	v_sub_f32_e32 v47, v47, v49
	v_add_f32_e32 v48, v29, v48
	v_exp_f32_e32 v31, v31
	v_add_f32_e32 v48, v45, v48
	v_exp_f32_e32 v47, v47
	v_add_f32_e32 v48, v30, v48
	v_add_f32_e32 v48, v46, v48
	v_add_f32_e32 v48, v31, v48
	v_add_f32_e32 v48, v47, v48
	s_waitcnt vmcnt(3) lgkmcnt(0)
	s_barrier
; __device__ __forceinline__ unsigned cvt_pk_bf16(float lo, float hi) { cvt_f32x2_t v = {lo, hi}; cvt_bf16x2_t b = __builtin_convertvector(v, cvt_bf16x2_t); return __builtin_bit_cast(unsigned, b); }
; template <bool FIRST, bool HAS_PREV> ...
;     ...
;     { u32x4 w;
;       w.x = pg8::cvt_pk_bf16(c0[0], c0[1]); w.y = pg8::cvt_pk_bf16(c0[2], c0[3]); w.z = pg8::cvt_pk_bf16(c0[4], c0[5]); w.w = pg8::cvt_pk_bf16(c0[6], c0[7]); pbp[0] = __builtin_bit_cast(bf16x8, w);
;       w.x = pg8::cvt_pk_bf16(c0[8], c0[9]); w.y = pg8::cvt_pk_bf16(c0[10], c0[11]); w.z = pg8::cvt_pk_bf16(c0[12], c0[13]); w.w = pg8::cvt_pk_bf16(c0[14], c0[15]); pbp[1] = __builtin_bit_cast(bf16x8, w);
;       w.x = pg8::cvt_pk_bf16(c1[0], c1[1]); w.y = pg8::cvt_pk_bf16(c1[2], c1[3]); w.z = pg8::cvt_pk_bf16(c1[4], c1[5]); w.w = pg8::cvt_pk_bf16(c1[6], c1[7]); pbp[2] = __builtin_bit_cast(bf16x8, w);
;       w.x = pg8::cvt_pk_bf16(c1[8], c1[9]); w.y = pg8::cvt_pk_bf16(c1[10], c1[11]); w.z = pg8::cvt_pk_bf16(c1[12], c1[13]); w.w = pg8::cvt_pk_bf16(c1[14], c1[15]); pbp[3] = __builtin_bit_cast(bf16x8, w); }
; __device__ __forceinline__ void attn_unit(LAS unsigned char* lds, const bf16* __restrict__ Qb, const bf16* __restrict__ Kb, const bf16* __restrict__ VT, bf16* __restrict__ Y,
;                                           const float* __restrict__ gsub, float lam, int b, int h, int qb, float* o1scr) {
;     ...
;         AttnState st; st.mrun = 0.f; st.l = 0.f;
;         bf16x8 pbp[4];
;         f32x16 sA, sB;
;         int s0 = 0, s1 = 1, s2 = 2;
	v_pk_add_f32 v[198:199], v[48:49], 0 op_sel_hi:[1,0]
	v_xor_b32_e32 v158, 0x80000000, v49
	v_mov_b32_e32 v159, v158
	v_mov_b32_e32 v160, v158
	v_mov_b32_e32 v161, v158
	v_mov_b32_e32 v162, v158
	v_mov_b32_e32 v163, v158
	v_mov_b32_e32 v164, v158
	v_mov_b32_e32 v165, v158
	v_mov_b32_e32 v166, v158
	v_mov_b32_e32 v167, v158
	v_mov_b32_e32 v168, v158
	v_mov_b32_e32 v169, v158
	v_mov_b32_e32 v170, v158
	v_mov_b32_e32 v171, v158
	v_mov_b32_e32 v172, v158
	v_mov_b32_e32 v173, v158
	v_add_u32_e32 v174, 0x6000, v210
	v_add_u32_e32 v175, 0x6000, v212
	v_add_u32_e32 v178, 0x6000, v214
	v_add_u32_e32 v179, 0x6000, v216
	v_cvt_pk_bf16_f32 v124, v16, v17
	v_cvt_pk_bf16_f32 v125, v18, v19
	v_cvt_pk_bf16_f32 v126, v20, v21
	v_cvt_pk_bf16_f32 v127, v22, v23
	v_cvt_pk_bf16_f32 v120, v24, v25
	v_cvt_pk_bf16_f32 v121, v26, v27
	v_cvt_pk_bf16_f32 v122, v28, v29
	v_cvt_pk_bf16_f32 v123, v30, v31
	v_cvt_pk_bf16_f32 v116, v32, v33
	v_cvt_pk_bf16_f32 v117, v34, v35
	v_cvt_pk_bf16_f32 v118, v36, v37
	v_cvt_pk_bf16_f32 v119, v38, v39
	v_cvt_pk_bf16_f32 v112, v40, v41
	v_cvt_pk_bf16_f32 v113, v42, v43
	v_cvt_pk_bf16_f32 v114, v44, v45
	v_cvt_pk_bf16_f32 v115, v46, v47
	v_mov_b64_e32 v[30:31], v[14:15]
	v_mov_b64_e32 v[46:47], v[14:15]
	v_mov_b64_e32 v[62:63], v[14:15]
	v_lshl_add_u64 v[200:201], v[194:195], 0, s[82:83]
	v_subrev_u32_e32 v193, s36, v194
	s_add_u32 s54, s36, s82
	s_addc_u32 s55, s37, s83
	v_subrev_u32_e32 v182, s30, v196
	s_mov_b32 s56, s30
	s_mov_b32 s57, s31
	v_add_u32_e32 v182, 0x23008000, v182
	v_add_u32_e32 v183, 0x2000, v182
	s_mov_b32 s44, 0
	s_mov_b32 s52, 2
	s_mov_b64 s[46:47], 0
	v_mov_b64_e32 v[28:29], v[12:13]
	v_mov_b64_e32 v[26:27], v[10:11]
	v_mov_b64_e32 v[24:25], v[8:9]
	v_mov_b64_e32 v[22:23], v[6:7]
	v_mov_b64_e32 v[20:21], v[4:5]
	v_mov_b64_e32 v[18:19], v[2:3]
	v_mov_b64_e32 v[16:17], v[0:1]
	v_mov_b64_e32 v[44:45], v[12:13]
	v_mov_b64_e32 v[42:43], v[10:11]
	v_mov_b64_e32 v[40:41], v[8:9]
	v_mov_b64_e32 v[38:39], v[6:7]
	v_mov_b64_e32 v[36:37], v[4:5]
	v_mov_b64_e32 v[34:35], v[2:3]
	v_mov_b64_e32 v[32:33], v[0:1]
	s_mov_b32 s53, 1
	v_mov_b64_e32 v[60:61], v[12:13]
	v_mov_b64_e32 v[58:59], v[10:11]
	v_mov_b64_e32 v[56:57], v[8:9]
	v_mov_b64_e32 v[54:55], v[6:7]
	v_mov_b64_e32 v[52:53], v[4:5]
	v_mov_b64_e32 v[50:51], v[2:3]
	v_mov_b64_e32 v[48:49], v[0:1]

; #define DSR128(dst, addr, off) asm volatile("ds_read_b128 %0, %1 offset:%2" : "=&v"(dst) : "v"(addr), "i"(off))
; #define ATT_EXPS(E) do { _Pragma("unroll") for (int j = 0; j < 8; ++j) { const int i = (E) * 8 + j; \
;         if (i < 16) { c0[i] = __builtin_amdgcn_exp2f(c0[i]); ps += c0[i]; } else { c1[i - 16] = __builtin_amdgcn_exp2f(c1[i - 16]); ps += c1[i - 16]; } } \
;         asm volatile("" : "+v"(c0), "+v"(c1), "+v"(ps)); __builtin_amdgcn_sched_barrier(0); } while (0)
; #define ATT_PV(KK, VF) do { _Pragma("unroll") for (int e = 0; e < 4; ++e) o[e] = __builtin_amdgcn_mfma_f32_32x32x16_bf16(VF[e], pbp[KK], o[e], 0, 0, 0); } while (0)
; #define ATT_TIE(N, VF) asm volatile("s_waitcnt lgkmcnt(" #N ")" : "+v"(VF[0]), "+v"(VF[1]), "+v"(VF[2]), "+v"(VF[3]))
; template <bool FIRST, bool HAS_PREV> ...
;     ...
;     if (HAS_PREV) {
;         __builtin_amdgcn_sched_barrier(0);
; #pragma unroll
;         for (int e = 0; e < 4; ++e) DSR128(vB[e], va[1], e * 4096);
;         ATT_TIE(4, vA); ATT_PV(0, vA); ATT_EXPS(0);
; #pragma unroll
;         for (int e = 0; e < 4; ++e) DSR128(vA[e], va[2], e * 4096);
;         ATT_TIE(4, vB); ATT_PV(1, vB); ATT_EXPS(1);
; #pragma unroll
;         for (int e = 0; e < 4; ++e) DSR128(vB[e], va[3], e * 4096);
;         ATT_TIE(4, vA); ATT_PV(2, vA); ATT_EXPS(2);
;         ATT_TIE(0, vB); ATT_PV(3, vB); ATT_EXPS(3);
;     } else {
; #pragma unroll
;         for (int i = 0; i < 16; ++i) { c0[i] = __builtin_amdgcn_exp2f(c0[i]); ps += c0[i]; c1[i] = __builtin_amdgcn_exp2f(c1[i]); ps += c1[i]; }
;     }
.Lu3_c_1:
	v_exp_f32_e32 v80, v80
	v_exp_f32_e32 v81, v81
	v_exp_f32_e32 v82, v82
	ds_read_b128 v[222:225], v175 offset:0
	ds_read_b128 v[226:229], v175 offset:4096
	ds_read_b128 v[230:233], v175 offset:8192
	ds_read_b128 v[234:237], v175 offset:12288
	s_waitcnt lgkmcnt(4)
	v_exp_f32_e32 v83, v83
	v_mfma_f32_32x32x16_bf16 v[48:63], v[140:143], v[124:127], v[48:63]
	v_exp_f32_e32 v84, v84
	v_exp_f32_e32 v85, v85
	v_add_f32_e32 v192, v80, v81
	v_add_f32_e32 v192, v82, v192
	v_mfma_f32_32x32x16_bf16 v[32:47], v[136:139], v[124:127], v[32:47]
	v_exp_f32_e32 v86, v86
	v_exp_f32_e32 v87, v87
	v_add_f32_e32 v192, v83, v192
	v_add_f32_e32 v192, v84, v192
	v_mfma_f32_32x32x16_bf16 v[16:31], v[132:135], v[124:127], v[16:31]
	v_exp_f32_e32 v88, v88
	v_exp_f32_e32 v89, v89
	v_add_f32_e32 v192, v85, v192
	v_add_f32_e32 v192, v86, v192
	v_mfma_f32_32x32x16_bf16 v[0:15], v[128:131], v[124:127], v[0:15]
	s_cmp_gt_u32 s53, 29
	s_cbranch_scc1 .Lu3_nok_1
	s_add_i32 m0, s33, 0x0
	s_nop 0
	global_load_lds_dwordx4 v193, s[54:55]
.Lu3_nok_1:
	ds_read_b128 v[124:127], v178 offset:0
	ds_read_b128 v[128:131], v178 offset:4096
	ds_read_b128 v[132:135], v178 offset:8192
	ds_read_b128 v[136:139], v178 offset:12288
	s_waitcnt lgkmcnt(4)
	v_exp_f32_e32 v90, v90
	v_exp_f32_e32 v91, v91
	v_add_f32_e32 v192, v87, v192
	v_add_f32_e32 v192, v88, v192
	v_mfma_f32_32x32x16_bf16 v[48:63], v[222:225], v[120:123], v[48:63]
	v_exp_f32_e32 v92, v92
	v_exp_f32_e32 v93, v93
	v_add_f32_e32 v192, v89, v192
	v_add_f32_e32 v192, v90, v192
	v_mfma_f32_32x32x16_bf16 v[32:47], v[226:229], v[120:123], v[32:47]
	v_exp_f32_e32 v94, v94
	v_exp_f32_e32 v95, v95
	v_add_f32_e32 v192, v91, v192
	v_add_f32_e32 v192, v92, v192
	v_mfma_f32_32x32x16_bf16 v[16:31], v[230:233], v[120:123], v[16:31]
	v_exp_f32_e32 v64, v64
	v_exp_f32_e32 v65, v65
	v_add_f32_e32 v192, v93, v192
	v_add_f32_e32 v192, v94, v192
	v_mfma_f32_32x32x16_bf16 v[0:15], v[234:237], v[120:123], v[0:15]
	s_cmp_eq_u32 s46, 0x78000
	s_cbranch_scc1 .Lu3_nov_1
	s_add_i32 m0, s33, 0xe000
	s_nop 0
	global_load_lds_dwordx4 v182, s[56:57]
	s_add_i32 m0, s33, 0x10000
	s_nop 0
	global_load_lds_dwordx4 v183, s[56:57]
.Lu3_nov_1:
	ds_read_b128 v[120:123], v179 offset:0
	ds_read_b128 v[140:143], v179 offset:4096
	ds_read_b128 v[222:225], v179 offset:8192
	ds_read_b128 v[226:229], v179 offset:12288
	s_waitcnt lgkmcnt(4)
	v_exp_f32_e32 v66, v66
	v_exp_f32_e32 v67, v67
	v_add_f32_e32 v192, v95, v192
	v_add_f32_e32 v192, v64, v192
	v_mfma_f32_32x32x16_bf16 v[48:63], v[124:127], v[116:119], v[48:63]
	v_exp_f32_e32 v68, v68
	v_exp_f32_e32 v69, v69
	v_add_f32_e32 v192, v65, v192
	v_add_f32_e32 v192, v66, v192
	v_mfma_f32_32x32x16_bf16 v[32:47], v[128:131], v[116:119], v[32:47]
	v_exp_f32_e32 v70, v70
	v_exp_f32_e32 v71, v71
	v_add_f32_e32 v192, v67, v192
	v_add_f32_e32 v192, v68, v192
	v_mfma_f32_32x32x16_bf16 v[16:31], v[132:135], v[116:119], v[16:31]
	v_exp_f32_e32 v72, v72
	v_exp_f32_e32 v73, v73
	v_add_f32_e32 v192, v69, v192
	v_add_f32_e32 v192, v70, v192
	v_mfma_f32_32x32x16_bf16 v[0:15], v[136:139], v[116:119], v[0:15]
	s_waitcnt lgkmcnt(0)
	v_exp_f32_e32 v74, v74
	v_exp_f32_e32 v75, v75
	v_add_f32_e32 v192, v71, v192
	v_add_f32_e32 v192, v72, v192
	v_mfma_f32_32x32x16_bf16 v[48:63], v[120:123], v[112:115], v[48:63]
	v_exp_f32_e32 v76, v76
	v_exp_f32_e32 v77, v77
	v_add_f32_e32 v192, v73, v192
	v_add_f32_e32 v192, v74, v192
	v_add_f32_e32 v192, v75, v192
	v_mfma_f32_32x32x16_bf16 v[32:47], v[140:143], v[112:115], v[32:47]
	v_exp_f32_e32 v78, v78
	v_exp_f32_e32 v79, v79
	v_add_f32_e32 v192, v76, v192
	v_add_f32_e32 v192, v77, v192
	v_mfma_f32_32x32x16_bf16 v[16:31], v[222:225], v[112:115], v[16:31]
	v_mfma_f32_32x32x16_bf16 v[0:15], v[226:229], v[112:115], v[0:15]
	v_add_f32_e32 v192, v78, v192
	v_add_f32_e32 v192, v79, v192
	s_cmp_lg_u32 s51, 0
	s_cbranch_scc1 .Lu3_resc_1
	v_add_f32_e32 v198, v198, v192

; #define DSR128(dst, addr, off) asm volatile("ds_read_b128 %0, %1 offset:%2" : "=&v"(dst) : "v"(addr), "i"(off))
; #define ATT_EXPS(E) do { _Pragma("unroll") for (int j = 0; j < 8; ++j) { const int i = (E) * 8 + j; \
;         if (i < 16) { c0[i] = __builtin_amdgcn_exp2f(c0[i]); ps += c0[i]; } else { c1[i - 16] = __builtin_amdgcn_exp2f(c1[i - 16]); ps += c1[i - 16]; } } \
;         asm volatile("" : "+v"(c0), "+v"(c1), "+v"(ps)); __builtin_amdgcn_sched_barrier(0); } while (0)
; #define ATT_PV(KK, VF) do { _Pragma("unroll") for (int e = 0; e < 4; ++e) o[e] = __builtin_amdgcn_mfma_f32_32x32x16_bf16(VF[e], pbp[KK], o[e], 0, 0, 0); } while (0)
; #define ATT_TIE(N, VF) asm volatile("s_waitcnt lgkmcnt(" #N ")" : "+v"(VF[0]), "+v"(VF[1]), "+v"(VF[2]), "+v"(VF[3]))
; template <bool FIRST, bool HAS_PREV> ...
;     ...
;     if (HAS_PREV) {
;         __builtin_amdgcn_sched_barrier(0);
; #pragma unroll
;         for (int e = 0; e < 4; ++e) DSR128(vB[e], va[1], e * 4096);
;         ATT_TIE(4, vA); ATT_PV(0, vA); ATT_EXPS(0);
; #pragma unroll
;         for (int e = 0; e < 4; ++e) DSR128(vA[e], va[2], e * 4096);
;         ATT_TIE(4, vB); ATT_PV(1, vB); ATT_EXPS(1);
; #pragma unroll
;         for (int e = 0; e < 4; ++e) DSR128(vB[e], va[3], e * 4096);
;         ATT_TIE(4, vA); ATT_PV(2, vA); ATT_EXPS(2);
;         ATT_TIE(0, vB); ATT_PV(3, vB); ATT_EXPS(3);
;     } else {
; #pragma unroll
;         for (int i = 0; i < 16; ++i) { c0[i] = __builtin_amdgcn_exp2f(c0[i]); ps += c0[i]; c1[i] = __builtin_amdgcn_exp2f(c1[i]); ps += c1[i]; }
;     }
.Lu3_c_2:
	v_exp_f32_e32 v80, v80
	v_exp_f32_e32 v81, v81
	v_exp_f32_e32 v82, v82
	ds_read_b128 v[222:225], v175 offset:16384
	ds_read_b128 v[226:229], v175 offset:20480
	ds_read_b128 v[230:233], v175 offset:24576
	ds_read_b128 v[234:237], v175 offset:28672
	s_waitcnt lgkmcnt(4)
	v_exp_f32_e32 v83, v83
	v_mfma_f32_32x32x16_bf16 v[48:63], v[140:143], v[124:127], v[48:63]
	v_exp_f32_e32 v84, v84
	v_exp_f32_e32 v85, v85
	v_add_f32_e32 v192, v80, v81
	v_add_f32_e32 v192, v82, v192
	v_mfma_f32_32x32x16_bf16 v[32:47], v[136:139], v[124:127], v[32:47]
	v_exp_f32_e32 v86, v86
	v_exp_f32_e32 v87, v87
	v_add_f32_e32 v192, v83, v192
	v_add_f32_e32 v192, v84, v192
	v_mfma_f32_32x32x16_bf16 v[16:31], v[132:135], v[124:127], v[16:31]
	v_exp_f32_e32 v88, v88
	v_exp_f32_e32 v89, v89
	v_add_f32_e32 v192, v85, v192
	v_add_f32_e32 v192, v86, v192
	v_mfma_f32_32x32x16_bf16 v[0:15], v[128:131], v[124:127], v[0:15]
	s_cmp_gt_u32 s53, 29
	s_cbranch_scc1 .Lu3_nok_2
	s_add_i32 m0, s33, 0x2000
	s_nop 0
	global_load_lds_dwordx4 v193, s[54:55]
.Lu3_nok_2:
	ds_read_b128 v[124:127], v178 offset:16384
	ds_read_b128 v[128:131], v178 offset:20480
	ds_read_b128 v[132:135], v178 offset:24576
	ds_read_b128 v[136:139], v178 offset:28672
	s_waitcnt lgkmcnt(4)
	v_exp_f32_e32 v90, v90
	v_exp_f32_e32 v91, v91
	v_add_f32_e32 v192, v87, v192
	v_add_f32_e32 v192, v88, v192
	v_mfma_f32_32x32x16_bf16 v[48:63], v[222:225], v[120:123], v[48:63]
	v_exp_f32_e32 v92, v92
	v_exp_f32_e32 v93, v93
	v_add_f32_e32 v192, v89, v192
	v_add_f32_e32 v192, v90, v192
	v_mfma_f32_32x32x16_bf16 v[32:47], v[226:229], v[120:123], v[32:47]
	v_exp_f32_e32 v94, v94
	v_exp_f32_e32 v95, v95
	v_add_f32_e32 v192, v91, v192
	v_add_f32_e32 v192, v92, v192
	v_mfma_f32_32x32x16_bf16 v[16:31], v[230:233], v[120:123], v[16:31]
	v_exp_f32_e32 v64, v64
	v_exp_f32_e32 v65, v65
	v_add_f32_e32 v192, v93, v192
	v_add_f32_e32 v192, v94, v192
	v_mfma_f32_32x32x16_bf16 v[0:15], v[234:237], v[120:123], v[0:15]
	s_cmp_eq_u32 s46, 0x78000
	s_cbranch_scc1 .Lu3_nov_2
	s_add_i32 m0, s33, 0x6000
	s_nop 0
	global_load_lds_dwordx4 v182, s[56:57]
	s_add_i32 m0, s33, 0x8000
	s_nop 0
	global_load_lds_dwordx4 v183, s[56:57]
.Lu3_nov_2:
	ds_read_b128 v[120:123], v179 offset:16384
	ds_read_b128 v[140:143], v179 offset:20480
	ds_read_b128 v[222:225], v179 offset:24576
	ds_read_b128 v[226:229], v179 offset:28672
	s_waitcnt lgkmcnt(4)
	v_exp_f32_e32 v66, v66
	v_exp_f32_e32 v67, v67
	v_add_f32_e32 v192, v95, v192
	v_add_f32_e32 v192, v64, v192
	v_mfma_f32_32x32x16_bf16 v[48:63], v[124:127], v[116:119], v[48:63]
	v_exp_f32_e32 v68, v68
	v_exp_f32_e32 v69, v69
	v_add_f32_e32 v192, v65, v192
	v_add_f32_e32 v192, v66, v192
	v_mfma_f32_32x32x16_bf16 v[32:47], v[128:131], v[116:119], v[32:47]
	v_exp_f32_e32 v70, v70
	v_exp_f32_e32 v71, v71
	v_add_f32_e32 v192, v67, v192
	v_add_f32_e32 v192, v68, v192
	v_mfma_f32_32x32x16_bf16 v[16:31], v[132:135], v[116:119], v[16:31]
	v_exp_f32_e32 v72, v72
	v_exp_f32_e32 v73, v73
	v_add_f32_e32 v192, v69, v192
	v_add_f32_e32 v192, v70, v192
	v_mfma_f32_32x32x16_bf16 v[0:15], v[136:139], v[116:119], v[0:15]
	s_waitcnt lgkmcnt(0)
	v_exp_f32_e32 v74, v74
	v_exp_f32_e32 v75, v75
	v_add_f32_e32 v192, v71, v192
	v_add_f32_e32 v192, v72, v192
	v_mfma_f32_32x32x16_bf16 v[48:63], v[120:123], v[112:115], v[48:63]
	v_exp_f32_e32 v76, v76
	v_exp_f32_e32 v77, v77
	v_add_f32_e32 v192, v73, v192
	v_add_f32_e32 v192, v74, v192
	v_add_f32_e32 v192, v75, v192
	v_mfma_f32_32x32x16_bf16 v[32:47], v[140:143], v[112:115], v[32:47]
	v_exp_f32_e32 v78, v78
	v_exp_f32_e32 v79, v79
	v_add_f32_e32 v192, v76, v192
	v_add_f32_e32 v192, v77, v192
	v_mfma_f32_32x32x16_bf16 v[16:31], v[222:225], v[112:115], v[16:31]
	v_mfma_f32_32x32x16_bf16 v[0:15], v[226:229], v[112:115], v[0:15]
	v_add_f32_e32 v192, v78, v192
	v_add_f32_e32 v192, v79, v192
	s_cmp_lg_u32 s51, 0
	s_cbranch_scc1 .Lu3_resc_2
	v_add_f32_e32 v198, v198, v192

; #define DSR128(dst, addr, off) asm volatile("ds_read_b128 %0, %1 offset:%2" : "=&v"(dst) : "v"(addr), "i"(off))
; #define ATT_EXPS(E) do { _Pragma("unroll") for (int j = 0; j < 8; ++j) { const int i = (E) * 8 + j; \
;         if (i < 16) { c0[i] = __builtin_amdgcn_exp2f(c0[i]); ps += c0[i]; } else { c1[i - 16] = __builtin_amdgcn_exp2f(c1[i - 16]); ps += c1[i - 16]; } } \
;         asm volatile("" : "+v"(c0), "+v"(c1), "+v"(ps)); __builtin_amdgcn_sched_barrier(0); } while (0)
; #define ATT_PV(KK, VF) do { _Pragma("unroll") for (int e = 0; e < 4; ++e) o[e] = __builtin_amdgcn_mfma_f32_32x32x16_bf16(VF[e], pbp[KK], o[e], 0, 0, 0); } while (0)
; #define ATT_TIE(N, VF) asm volatile("s_waitcnt lgkmcnt(" #N ")" : "+v"(VF[0]), "+v"(VF[1]), "+v"(VF[2]), "+v"(VF[3]))
; template <bool FIRST, bool HAS_PREV> ...
;     ...
;     if (HAS_PREV) {
;         __builtin_amdgcn_sched_barrier(0);
; #pragma unroll
;         for (int e = 0; e < 4; ++e) DSR128(vB[e], va[1], e * 4096);
;         ATT_TIE(4, vA); ATT_PV(0, vA); ATT_EXPS(0);
; #pragma unroll
;         for (int e = 0; e < 4; ++e) DSR128(vA[e], va[2], e * 4096);
;         ATT_TIE(4, vB); ATT_PV(1, vB); ATT_EXPS(1);
; #pragma unroll
;         for (int e = 0; e < 4; ++e) DSR128(vB[e], va[3], e * 4096);
;         ATT_TIE(4, vA); ATT_PV(2, vA); ATT_EXPS(2);
;         ATT_TIE(0, vB); ATT_PV(3, vB); ATT_EXPS(3);
;     } else {
; #pragma unroll
;         for (int i = 0; i < 16; ++i) { c0[i] = __builtin_amdgcn_exp2f(c0[i]); ps += c0[i]; c1[i] = __builtin_amdgcn_exp2f(c1[i]); ps += c1[i]; }
;     }
.Lu3_c_0:
	v_exp_f32_e32 v80, v80
	v_exp_f32_e32 v81, v81
	v_exp_f32_e32 v82, v82
	ds_read_b128 v[222:225], v175 offset:32768
	ds_read_b128 v[226:229], v175 offset:36864
	ds_read_b128 v[230:233], v175 offset:40960
	ds_read_b128 v[234:237], v175 offset:45056
	s_waitcnt lgkmcnt(4)
	v_exp_f32_e32 v83, v83
	v_mfma_f32_32x32x16_bf16 v[48:63], v[140:143], v[124:127], v[48:63]
	v_exp_f32_e32 v84, v84
	v_exp_f32_e32 v85, v85
	v_add_f32_e32 v192, v80, v81
	v_add_f32_e32 v192, v82, v192
	v_mfma_f32_32x32x16_bf16 v[32:47], v[136:139], v[124:127], v[32:47]
	v_exp_f32_e32 v86, v86
	v_exp_f32_e32 v87, v87
	v_add_f32_e32 v192, v83, v192
	v_add_f32_e32 v192, v84, v192
	v_mfma_f32_32x32x16_bf16 v[16:31], v[132:135], v[124:127], v[16:31]
	v_exp_f32_e32 v88, v88
	v_exp_f32_e32 v89, v89
	v_add_f32_e32 v192, v85, v192
	v_add_f32_e32 v192, v86, v192
	v_mfma_f32_32x32x16_bf16 v[0:15], v[128:131], v[124:127], v[0:15]
	s_cmp_gt_u32 s53, 29
	s_cbranch_scc1 .Lu3_nok_0
	s_add_i32 m0, s33, 0x4000
	s_nop 0
	global_load_lds_dwordx4 v193, s[54:55]
.Lu3_nok_0:
	ds_read_b128 v[124:127], v178 offset:32768
	ds_read_b128 v[128:131], v178 offset:36864
	ds_read_b128 v[132:135], v178 offset:40960
	ds_read_b128 v[136:139], v178 offset:45056
	s_waitcnt lgkmcnt(4)
	v_exp_f32_e32 v90, v90
	v_exp_f32_e32 v91, v91
	v_add_f32_e32 v192, v87, v192
	v_add_f32_e32 v192, v88, v192
	v_mfma_f32_32x32x16_bf16 v[48:63], v[222:225], v[120:123], v[48:63]
	v_exp_f32_e32 v92, v92
	v_exp_f32_e32 v93, v93
	v_add_f32_e32 v192, v89, v192
	v_add_f32_e32 v192, v90, v192
	v_mfma_f32_32x32x16_bf16 v[32:47], v[226:229], v[120:123], v[32:47]
	v_exp_f32_e32 v94, v94
	v_exp_f32_e32 v95, v95
	v_add_f32_e32 v192, v91, v192
	v_add_f32_e32 v192, v92, v192
	v_mfma_f32_32x32x16_bf16 v[16:31], v[230:233], v[120:123], v[16:31]
	v_exp_f32_e32 v64, v64
	v_exp_f32_e32 v65, v65
	v_add_f32_e32 v192, v93, v192
	v_add_f32_e32 v192, v94, v192
	v_mfma_f32_32x32x16_bf16 v[0:15], v[234:237], v[120:123], v[0:15]
	s_cmp_eq_u32 s46, 0x78000
	s_cbranch_scc1 .Lu3_nov_0
	s_add_i32 m0, s33, 0xa000
	s_nop 0
	global_load_lds_dwordx4 v182, s[56:57]
	s_add_i32 m0, s33, 0xc000
	s_nop 0
	global_load_lds_dwordx4 v183, s[56:57]
.Lu3_nov_0:
	ds_read_b128 v[120:123], v179 offset:32768
	ds_read_b128 v[140:143], v179 offset:36864
	ds_read_b128 v[222:225], v179 offset:40960
	ds_read_b128 v[226:229], v179 offset:45056
	s_waitcnt lgkmcnt(4)
	v_exp_f32_e32 v66, v66
	v_exp_f32_e32 v67, v67
	v_add_f32_e32 v192, v95, v192
	v_add_f32_e32 v192, v64, v192
	v_mfma_f32_32x32x16_bf16 v[48:63], v[124:127], v[116:119], v[48:63]
	v_exp_f32_e32 v68, v68
	v_exp_f32_e32 v69, v69
	v_add_f32_e32 v192, v65, v192
	v_add_f32_e32 v192, v66, v192
	v_mfma_f32_32x32x16_bf16 v[32:47], v[128:131], v[116:119], v[32:47]
	v_exp_f32_e32 v70, v70
	v_exp_f32_e32 v71, v71
	v_add_f32_e32 v192, v67, v192
	v_add_f32_e32 v192, v68, v192
	v_mfma_f32_32x32x16_bf16 v[16:31], v[132:135], v[116:119], v[16:31]
	v_exp_f32_e32 v72, v72
	v_exp_f32_e32 v73, v73
	v_add_f32_e32 v192, v69, v192
	v_add_f32_e32 v192, v70, v192
	v_mfma_f32_32x32x16_bf16 v[0:15], v[136:139], v[116:119], v[0:15]
	s_waitcnt lgkmcnt(0)
	v_exp_f32_e32 v74, v74
	v_exp_f32_e32 v75, v75
	v_add_f32_e32 v192, v71, v192
	v_add_f32_e32 v192, v72, v192
	v_mfma_f32_32x32x16_bf16 v[48:63], v[120:123], v[112:115], v[48:63]
	v_exp_f32_e32 v76, v76
	v_exp_f32_e32 v77, v77
	v_add_f32_e32 v192, v73, v192
	v_add_f32_e32 v192, v74, v192
	v_add_f32_e32 v192, v75, v192
	v_mfma_f32_32x32x16_bf16 v[32:47], v[140:143], v[112:115], v[32:47]
	v_exp_f32_e32 v78, v78
	v_exp_f32_e32 v79, v79
	v_add_f32_e32 v192, v76, v192
	v_add_f32_e32 v192, v77, v192
	v_mfma_f32_32x32x16_bf16 v[16:31], v[222:225], v[112:115], v[16:31]
	v_mfma_f32_32x32x16_bf16 v[0:15], v[226:229], v[112:115], v[0:15]
	v_add_f32_e32 v192, v78, v192
	v_add_f32_e32 v192, v79, v192
	s_cmp_lg_u32 s51, 0
	s_cbranch_scc1 .Lu3_resc_0
	v_add_f32_e32 v198, v198, v192
